# masked window-attention loop: both K/V prefetch address blocks -> scalar 64-bit base adjust + 32-bit offsets with SGPR-base loads (on top of the diff-loop and short-loop address rewrites)
# speedup vs baseline: 1.0108x; 1.0026x over previous
.LBB0_200:
	s_nop 0
	s_lshl_b32 s42, s75, 6
	s_ashr_i32 s43, s42, 31
	s_lshl_b64 s[42:43], s[42:43], 1
	s_add_u32 s68, s68, s42
	s_addc_u32 s69, s69, s43
	s_lshl_b64 s[42:43], s[42:43], 6
	s_add_u32 s70, s70, s42
	s_addc_u32 s71, s71, s43
	v_lshrrev_b32_e32 v36, 3, v204
	v_lshlrev_b32_e32 v96, 4, v204
	v_and_b32_e32 v96, 0x70, v96
	v_lshl_add_u32 v34, v36, 7, v96
	v_mul_u32_u24_e32 v35, s40, v36
	v_lshl_add_u32 v35, v35, 1, v96
	s_nop 0
	global_load_dwordx4 v[88:91], v34, s[70:71]
	s_nop 0
	global_load_dwordx4 v[92:95], v35, s[68:69]
	s_and_b64 vcc, exec, s[0:1]
	s_cbranch_vccnz .LBB0_194

.LBB0_216:
	s_nop 0
	s_lshl_b32 s42, s73, 6
	s_ashr_i32 s43, s42, 31
	s_lshl_b64 s[42:43], s[42:43], 1
	s_add_u32 s40, s40, s42
	s_addc_u32 s41, s41, s43
	s_lshl_b64 s[42:43], s[42:43], 6
	s_add_u32 s68, s68, s42
	s_addc_u32 s69, s69, s43
	v_lshrrev_b32_e32 v36, 3, v204
	v_lshlrev_b32_e32 v96, 4, v204
	v_and_b32_e32 v96, 0x70, v96
	v_lshl_add_u32 v34, v36, 7, v96
	v_mul_u32_u24_e32 v35, s30, v36
	v_lshl_add_u32 v35, v35, 1, v96
	s_nop 0
	global_load_dwordx4 v[80:83], v34, s[68:69]
	s_nop 0
	global_load_dwordx4 v[84:87], v35, s[40:41]
